# v54 + layer-A attention tile loop head reordered: first QK ds_reads issued before the next-tile global loads (loop-edge edit)
# speedup vs baseline: 1.0041x; 1.0021x over previous
.LBB0_619:
	s_add_i32 s25, s26, 1
	s_cmp_lt_i32 s25, s24
	s_cselect_b64 s[12:13], -1, 0
	s_and_b32 s26, s26, 1
	s_mul_i32 s27, s26, 0x4400
	v_add3_u32 v0, v185, s27, v186
	ds_read_b128 v[4:7], v0
	ds_read_b128 v[8:11], v0 offset:32
	ds_read_b128 v[12:15], v0 offset:8704
	ds_read_b128 v[196:199], v0 offset:8736
	s_cmp_ge_i32 s25, s24
	s_cbranch_scc1 .LBB0_621
	v_lshl_add_u64 v[2:3], s[52:53], 1, v[160:161]
	v_lshl_add_u64 v[254:255], v[2:3], 0, v[162:163]
	v_lshl_add_u64 v[2:3], v[2:3], 0, v[164:165]
	global_load_dwordx4 v[112:115], v[168:169], off
	global_load_dwordx4 v[120:123], v[178:179], off
	global_load_dwordx4 v[116:119], v[254:255], off
	global_load_dwordx4 v[124:127], v[2:3], off
	s_nop 0
	global_load_dwordx2 v[2:3], v[180:181], off
.LBB0_621:
	s_waitcnt lgkmcnt(3)
	v_mfma_f32_32x32x16_bf16 v[96:111], v[4:7], v[152:155], 0
	s_waitcnt lgkmcnt(1)
	v_mfma_f32_32x32x16_bf16 v[80:95], v[12:15], v[152:155], 0
	v_mfma_f32_32x32x16_bf16 v[96:111], v[8:11], v[136:139], v[96:111]
	s_waitcnt lgkmcnt(0)
	v_mfma_f32_32x32x16_bf16 v[80:95], v[196:199], v[136:139], v[80:95]
	ds_read_b128 v[4:7], v0 offset:64
	ds_read_b128 v[8:11], v0 offset:96
	ds_read_b128 v[12:15], v0 offset:8768
	ds_read_b128 v[196:199], v0 offset:8800
	s_waitcnt lgkmcnt(3)
	v_mfma_f32_32x32x16_bf16 v[96:111], v[4:7], v[148:151], v[96:111]
	s_waitcnt lgkmcnt(1)
	v_mfma_f32_32x32x16_bf16 v[80:95], v[12:15], v[148:151], v[80:95]
	v_mfma_f32_32x32x16_bf16 v[96:111], v[8:11], v[132:135], v[96:111]
	s_waitcnt lgkmcnt(0)
	v_mfma_f32_32x32x16_bf16 v[80:95], v[196:199], v[132:135], v[80:95]
	ds_read_b128 v[4:7], v0 offset:128
	ds_read_b128 v[8:11], v0 offset:160
	ds_read_b128 v[12:15], v0 offset:8832
	ds_read_b128 v[196:199], v0 offset:8864
	s_waitcnt lgkmcnt(3)
	v_mfma_f32_32x32x16_bf16 v[96:111], v[4:7], v[144:147], v[96:111]
	s_waitcnt lgkmcnt(1)
	v_mfma_f32_32x32x16_bf16 v[80:95], v[12:15], v[144:147], v[80:95]
	v_mfma_f32_32x32x16_bf16 v[96:111], v[8:11], v[128:131], v[96:111]
	s_waitcnt lgkmcnt(0)
	v_mfma_f32_32x32x16_bf16 v[80:95], v[196:199], v[128:131], v[80:95]
	ds_read_b128 v[4:7], v0 offset:192
	ds_read_b128 v[8:11], v0 offset:224
	ds_read_b128 v[12:15], v0 offset:8896
	ds_read_b128 v[196:199], v0 offset:8928
	v_lshrrev_b32_e32 v0, v187, v166
	s_waitcnt lgkmcnt(3)
	v_mfma_f32_32x32x16_bf16 v[96:111], v[4:7], v[140:143], v[96:111]
	v_bfe_i32 v5, v0, 2, 1
	v_bfe_i32 v4, v0, 0, 1
	s_waitcnt lgkmcnt(1)
	v_mfma_f32_32x32x16_bf16 v[80:95], v[12:15], v[140:143], v[80:95]
	v_mfma_f32_32x32x16_bf16 v[96:111], v[8:11], v[156:159], v[96:111]
	s_waitcnt lgkmcnt(0)
	v_mfma_f32_32x32x16_bf16 v[80:95], v[196:199], v[156:159], v[80:95]
	s_nop 9
	v_bitop3_b32 v198, v98, s70, v5 bitop3:0xe4
	v_bfe_i32 v5, v0, 3, 1
	v_bitop3_b32 v199, v99, s70, v5 bitop3:0xe4
	v_bfe_i32 v5, v0, 8, 1
	v_bitop3_b32 v200, v100, s70, v5 bitop3:0xe4
	v_bfe_i32 v5, v0, 9, 1
	v_bitop3_b32 v201, v101, s70, v5 bitop3:0xe4
	v_bfe_i32 v5, v0, 10, 1
	v_bitop3_b32 v196, v96, s70, v4 bitop3:0xe4
	v_bfe_i32 v4, v0, 1, 1
	v_bitop3_b32 v202, v102, s70, v5 bitop3:0xe4
	v_bfe_i32 v5, v0, 11, 1
	v_bitop3_b32 v197, v97, s70, v4 bitop3:0xe4
	v_bitop3_b32 v166, v103, s70, v5 bitop3:0xe4
	v_bfe_i32 v5, v0, 16, 1
	v_max3_f32 v4, v196, s70, v197
	v_bitop3_b32 v100, v104, s70, v5 bitop3:0xe4
	v_bfe_i32 v5, v0, 17, 1
	v_max3_f32 v4, v4, v198, v199
	v_bitop3_b32 v101, v105, s70, v5 bitop3:0xe4
	v_bfe_i32 v5, v0, 18, 1
	v_max3_f32 v4, v4, v200, v201
	v_bitop3_b32 v98, v106, s70, v5 bitop3:0xe4
	v_bfe_i32 v5, v0, 19, 1
	v_max3_f32 v4, v4, v202, v166
	v_bitop3_b32 v102, v107, s70, v5 bitop3:0xe4
	v_bfe_i32 v5, v0, 24, 1
	v_max3_f32 v4, v4, v100, v101
	v_bitop3_b32 v103, v108, s70, v5 bitop3:0xe4
	v_bfe_i32 v5, v0, 25, 1
	v_max3_f32 v4, v4, v98, v102
	v_bitop3_b32 v99, v109, s70, v5 bitop3:0xe4
	v_bfe_i32 v5, v0, 26, 1
	v_bfe_i32 v0, v0, 27, 1
	v_max3_f32 v4, v4, v103, v99
	v_bitop3_b32 v104, v110, s70, v5 bitop3:0xe4
	v_bitop3_b32 v97, v111, s70, v0 bitop3:0xe4
	v_lshrrev_b32_e32 v105, v187, v167
	v_max3_f32 v0, v4, v104, v97
	v_bfe_i32 v4, v105, 0, 1
	v_bitop3_b32 v96, v80, s70, v4 bitop3:0xe4
	v_bfe_i32 v4, v105, 1, 1
	v_bitop3_b32 v81, v81, s70, v4 bitop3:0xe4
	v_bfe_i32 v4, v105, 2, 1
	v_bitop3_b32 v14, v82, s70, v4 bitop3:0xe4
	v_bfe_i32 v4, v105, 3, 1
	v_bitop3_b32 v15, v83, s70, v4 bitop3:0xe4
	v_bfe_i32 v4, v105, 8, 1
	v_bitop3_b32 v80, v84, s70, v4 bitop3:0xe4
	v_bfe_i32 v4, v105, 9, 1
	v_bitop3_b32 v12, v85, s70, v4 bitop3:0xe4
	v_bfe_i32 v4, v105, 10, 1
	v_bitop3_b32 v13, v86, s70, v4 bitop3:0xe4
	v_bfe_i32 v4, v105, 11, 1
	v_bitop3_b32 v11, v87, s70, v4 bitop3:0xe4
	v_bfe_i32 v4, v105, 16, 1
	v_max3_f32 v0, v0, v96, v81
	v_bitop3_b32 v9, v88, s70, v4 bitop3:0xe4
	v_bfe_i32 v4, v105, 17, 1
	v_max3_f32 v0, v0, v14, v15
	v_bitop3_b32 v10, v89, s70, v4 bitop3:0xe4
	v_bfe_i32 v4, v105, 18, 1
	v_max3_f32 v0, v0, v80, v12
	v_bitop3_b32 v6, v90, s70, v4 bitop3:0xe4
	v_bfe_i32 v4, v105, 19, 1
	v_max3_f32 v0, v0, v13, v11
	v_bitop3_b32 v7, v91, s70, v4 bitop3:0xe4
	v_bfe_i32 v4, v105, 24, 1
	v_max3_f32 v0, v0, v9, v10
	v_bitop3_b32 v8, v92, s70, v4 bitop3:0xe4
	v_bfe_i32 v4, v105, 25, 1
	v_max3_f32 v0, v0, v6, v7
	v_bitop3_b32 v4, v93, s70, v4 bitop3:0xe4
	v_max3_f32 v82, v0, v8, v4
	v_bfe_i32 v0, v105, 26, 1
	v_bitop3_b32 v5, v94, s70, v0 bitop3:0xe4
	v_bfe_i32 v0, v105, 27, 1
	v_bitop3_b32 v0, v95, s70, v0 bitop3:0xe4
	v_max3_f32 v82, v82, v5, v0
	v_mov_b32_e32 v83, v82
	s_nop 1
	v_permlane32_swap_b32_e32 v83, v82
	v_max_f32_e32 v82, v82, v83
	v_add_f32_e32 v83, 0x41000000, v183
	v_cmp_gt_f32_e32 vcc, v82, v83
	s_cbranch_vccz .LBB0_623
	v_max_f32_e32 v82, v82, v82
	v_max_f32_e32 v83, v183, v183
	v_max_f32_e32 v83, v83, v82
	v_cmp_neq_f32_e32 vcc, s70, v83
	s_nop 1
	v_cndmask_b32_e32 v82, 0, v83, vcc
	v_sub_f32_e32 v82, v183, v82
	v_exp_f32_e32 v82, v82
	v_mov_b32_e32 v183, v83
	v_mul_f32_e32 v182, v182, v82
	v_pk_mul_f32 v[78:79], v[78:79], v[82:83] op_sel_hi:[1,0]
	v_pk_mul_f32 v[76:77], v[76:77], v[82:83] op_sel_hi:[1,0]
	v_pk_mul_f32 v[74:75], v[74:75], v[82:83] op_sel_hi:[1,0]
	v_pk_mul_f32 v[72:73], v[72:73], v[82:83] op_sel_hi:[1,0]
	v_pk_mul_f32 v[70:71], v[70:71], v[82:83] op_sel_hi:[1,0]
	v_pk_mul_f32 v[68:69], v[68:69], v[82:83] op_sel_hi:[1,0]
	v_pk_mul_f32 v[66:67], v[66:67], v[82:83] op_sel_hi:[1,0]
	v_pk_mul_f32 v[64:65], v[64:65], v[82:83] op_sel_hi:[1,0]
	v_pk_mul_f32 v[62:63], v[62:63], v[82:83] op_sel_hi:[1,0]
	v_pk_mul_f32 v[60:61], v[60:61], v[82:83] op_sel_hi:[1,0]
	v_pk_mul_f32 v[58:59], v[58:59], v[82:83] op_sel_hi:[1,0]
	v_pk_mul_f32 v[56:57], v[56:57], v[82:83] op_sel_hi:[1,0]
	v_pk_mul_f32 v[54:55], v[54:55], v[82:83] op_sel_hi:[1,0]
	v_pk_mul_f32 v[52:53], v[52:53], v[82:83] op_sel_hi:[1,0]
	v_pk_mul_f32 v[50:51], v[50:51], v[82:83] op_sel_hi:[1,0]
	v_pk_mul_f32 v[48:49], v[48:49], v[82:83] op_sel_hi:[1,0]
	v_pk_mul_f32 v[46:47], v[46:47], v[82:83] op_sel_hi:[1,0]
	v_pk_mul_f32 v[44:45], v[44:45], v[82:83] op_sel_hi:[1,0]
	v_pk_mul_f32 v[42:43], v[42:43], v[82:83] op_sel_hi:[1,0]
	v_pk_mul_f32 v[40:41], v[40:41], v[82:83] op_sel_hi:[1,0]
	v_pk_mul_f32 v[38:39], v[38:39], v[82:83] op_sel_hi:[1,0]
	v_pk_mul_f32 v[36:37], v[36:37], v[82:83] op_sel_hi:[1,0]
	v_pk_mul_f32 v[34:35], v[34:35], v[82:83] op_sel_hi:[1,0]
	v_pk_mul_f32 v[32:33], v[32:33], v[82:83] op_sel_hi:[1,0]
	v_pk_mul_f32 v[30:31], v[30:31], v[82:83] op_sel_hi:[1,0]
	v_pk_mul_f32 v[28:29], v[28:29], v[82:83] op_sel_hi:[1,0]
	v_pk_mul_f32 v[26:27], v[26:27], v[82:83] op_sel_hi:[1,0]
	v_pk_mul_f32 v[24:25], v[24:25], v[82:83] op_sel_hi:[1,0]
	v_pk_mul_f32 v[22:23], v[22:23], v[82:83] op_sel_hi:[1,0]
	v_pk_mul_f32 v[20:21], v[20:21], v[82:83] op_sel_hi:[1,0]
	v_pk_mul_f32 v[18:19], v[18:19], v[82:83] op_sel_hi:[1,0]
	v_pk_mul_f32 v[16:17], v[16:17], v[82:83] op_sel_hi:[1,0]

	.amdhsa_kernel _Z8yoco_fwd4Args
		.amdhsa_group_segment_fixed_size 0
		.amdhsa_private_segment_fixed_size 0
		.amdhsa_kernarg_size 464
		.amdhsa_user_sgpr_count 2
		.amdhsa_user_sgpr_dispatch_ptr 0
		.amdhsa_user_sgpr_queue_ptr 0
		.amdhsa_user_sgpr_kernarg_segment_ptr 1
		.amdhsa_user_sgpr_dispatch_id 0
		.amdhsa_user_sgpr_kernarg_preload_length 0
		.amdhsa_user_sgpr_kernarg_preload_offset 0
		.amdhsa_user_sgpr_private_segment_size 0
		.amdhsa_uses_dynamic_stack 0
		.amdhsa_enable_private_segment 0
		.amdhsa_system_sgpr_workgroup_id_x 1
		.amdhsa_system_sgpr_workgroup_id_y 0
		.amdhsa_system_sgpr_workgroup_id_z 0
		.amdhsa_system_sgpr_workgroup_info 0
		.amdhsa_system_vgpr_workitem_id 2
		.amdhsa_next_free_vgpr 256
		.amdhsa_next_free_sgpr 100
		.amdhsa_accum_offset 256
		.amdhsa_reserve_vcc 1
		.amdhsa_float_round_mode_32 0
		.amdhsa_float_round_mode_16_64 0
		.amdhsa_float_denorm_mode_32 3
		.amdhsa_float_denorm_mode_16_64 3
		.amdhsa_dx10_clamp 1
		.amdhsa_ieee_mode 1
		.amdhsa_fp16_overflow 0
		.amdhsa_tg_split 0
		.amdhsa_exception_fp_ieee_invalid_op 0
		.amdhsa_exception_fp_denorm_src 0
		.amdhsa_exception_fp_ieee_div_zero 0
		.amdhsa_exception_fp_ieee_overflow 0
		.amdhsa_exception_fp_ieee_underflow 0
		.amdhsa_exception_fp_ieee_inexact 0
		.amdhsa_exception_int_div_zero 0
	.end_amdhsa_kernel

amdhsa.kernels:
  - .agpr_count:     0
    .args:
      - .offset:         0
        .size:           208
        .value_kind:     by_value
      - .offset:         208
        .size:           4
        .value_kind:     hidden_block_count_x
      - .offset:         212
        .size:           4
        .value_kind:     hidden_block_count_y
      - .offset:         216
        .size:           4
        .value_kind:     hidden_block_count_z
      - .offset:         220
        .size:           2
        .value_kind:     hidden_group_size_x
      - .offset:         222
        .size:           2
        .value_kind:     hidden_group_size_y
      - .offset:         224
        .size:           2
        .value_kind:     hidden_group_size_z
      - .offset:         226
        .size:           2
        .value_kind:     hidden_remainder_x
      - .offset:         228
        .size:           2
        .value_kind:     hidden_remainder_y
      - .offset:         230
        .size:           2
        .value_kind:     hidden_remainder_z
      - .offset:         248
        .size:           8
        .value_kind:     hidden_global_offset_x
      - .offset:         256
        .size:           8
        .value_kind:     hidden_global_offset_y
      - .offset:         264
        .size:           8
        .value_kind:     hidden_global_offset_z
      - .offset:         272
        .size:           2
        .value_kind:     hidden_grid_dims
      - .offset:         296
        .size:           8
        .value_kind:     hidden_multigrid_sync_arg
      - .offset:         328
        .size:           4
        .value_kind:     hidden_dynamic_lds_size
    .group_segment_fixed_size: 0
    .kernarg_segment_align: 8
    .kernarg_segment_size: 464
    .language:       OpenCL C
    .language_version:
      - 2
      - 0
    .max_flat_workgroup_size: 512
    .name:           _Z8yoco_fwd4Args
    .private_segment_fixed_size: 0
    .sgpr_count:     106
    .sgpr_spill_count: 294
    .symbol:         _Z8yoco_fwd4Args.kd
    .uniform_work_group_size: 1
    .uses_dynamic_stack: false
    .vgpr_count:     256
    .vgpr_spill_count: 0
    .wavefront_size: 64
